# epilogue de-serialisation: attention+SGU gain-vector loads issued together (16 serial load+wait pairs removed per unit), store ladders read LDS in one burst
# speedup vs baseline: 1.0049x; 1.0049x over previous
; __device__ __forceinline__ unsigned cvt_pk_bf16(float lo, float hi) { unsigned r; asm volatile("v_cvt_pk_bf16_f32 %0, %1, %2" : "=v"(r) : "v"(lo), "v"(hi)); return r; }
; #define LAS __attribute__((address_space(3)))
; __device__ __forceinline__ void attn_units(LAS unsigned char* lds, const bf16* QB, const bf16* KB, const bf16* VT, const bf16* VTc, bf16* MIX, const float* sink, const float* gmix,
;                                            int nunits, int G, int vb, int tid) {
;     ...
;         for (int qs = 0; qs < 2; ++qs) { float tot = 0.f;
; #pragma unroll
;             for (int w = 0; w < 8; ++w) tot += red[w * 64 + qs * 32 + c];
;             const float rn = rsqrtf(tot * (1.f / 512.f) + EPSN);
; #pragma unroll
;             for (int dt = 0; dt < 2; ++dt)
; #pragma unroll
;                 for (int rg = 0; rg < 4; ++rg) { const f32x4 gm = *(const f32x4*)(gmix + wave * 64 + dt * 32 + rg * 8 + hh * 4);
;                     v2u w; w.x = cvt_pk_bf16(o[qs][dt][4 * rg] * rn * gm[0], o[qs][dt][4 * rg + 1] * rn * gm[1]); w.y = cvt_pk_bf16(o[qs][dt][4 * rg + 2] * rn * gm[2], o[qs][dt][4 * rg + 3] * rn * gm[3]);
;                     *(LAS v2u*)(otile + (qs * 32 + c) * 72 + dt * 32 + rg * 8 + hh * 4) = w; } }
.LBB0_293:
	s_or_b64 exec, exec, s[4:5]
	s_waitcnt lgkmcnt(0)
	s_barrier
	ds_read2st64_b32 v[50:51], v235 offset1:1
	s_add_i32 s25, s25, s62
	s_cmp_lt_i32 s25, s24
	s_waitcnt lgkmcnt(0)
	v_add_f32_e32 v50, 0, v50
	v_add_f32_e32 v52, v50, v51
	ds_read2st64_b32 v[50:51], v235 offset0:2 offset1:3
	s_waitcnt lgkmcnt(0)
	v_add_f32_e32 v50, v52, v50
	v_add_f32_e32 v52, v50, v51
	ds_read2st64_b32 v[50:51], v235 offset0:4 offset1:5
	s_waitcnt lgkmcnt(0)
	v_add_f32_e32 v50, v52, v50
	v_add_f32_e32 v52, v50, v51
	ds_read2st64_b32 v[50:51], v235 offset0:6 offset1:7
	s_waitcnt lgkmcnt(0)
	v_add_f32_e32 v50, v52, v50
	v_add_f32_e32 v50, v50, v51
	v_fmamk_f32 v50, v50, 0x3b000000, v178
	v_cmp_gt_f32_e32 vcc, s29, v50
	v_mul_f32_e32 v51, 0x4b800000, v50
	s_nop 0
	v_cndmask_b32_e32 v50, v50, v51, vcc
	v_rsq_f32_e32 v50, v50
	s_nop 0
	v_mul_f32_e32 v51, 0x45800000, v50
	v_cndmask_b32_e32 v50, v50, v51, vcc
	v_mul_f32_e32 v51, v76, v50
	v_mul_f32_e32 v46, v46, v50
	v_mul_f32_e32 v47, v47, v50
	v_mul_f32_e32 v44, v44, v50
	v_mul_f32_e32 v45, v45, v50
	v_mul_f32_e32 v42, v42, v50
	v_mul_f32_e32 v43, v43, v50
	v_mul_f32_e32 v40, v40, v50
	v_mul_f32_e32 v41, v41, v50
	v_mul_f32_e32 v38, v38, v50
	v_mul_f32_e32 v39, v39, v50
	v_mul_f32_e32 v36, v36, v50
	v_mul_f32_e32 v37, v37, v50
	v_mul_f32_e32 v34, v34, v50
	v_mul_f32_e32 v35, v35, v50
	v_mul_f32_e32 v32, v32, v50
	v_mul_f32_e32 v33, v33, v50
	s_waitcnt vmcnt(0)
	v_mul_f32_e32 v51, v96, v51
	v_mul_f32_e32 v52, v77, v50
	v_mul_f32_e32 v52, v97, v52
	v_mul_f32_e32 v53, v75, v50
	v_cvt_pk_bf16_f32 v52, v51, v52
	v_mul_f32_e32 v51, v74, v50
	v_mul_f32_e32 v53, v99, v53
	v_mul_f32_e32 v51, v98, v51
	v_cvt_pk_bf16_f32 v53, v51, v53
	ds_write_b64 v244, v[52:53]
	v_mul_f32_e32 v51, v72, v50
	s_waitcnt vmcnt(0)
	v_mul_f32_e32 v51, v100, v51
	v_mul_f32_e32 v52, v73, v50
	v_mul_f32_e32 v52, v101, v52
	v_mul_f32_e32 v53, v71, v50
	v_cvt_pk_bf16_f32 v52, v51, v52
	v_mul_f32_e32 v51, v70, v50
	v_mul_f32_e32 v53, v103, v53
	v_mul_f32_e32 v51, v102, v51
	v_cvt_pk_bf16_f32 v53, v51, v53
	ds_write_b64 v244, v[52:53] offset:16
	v_mul_f32_e32 v51, v68, v50
	s_waitcnt vmcnt(0)
	v_mul_f32_e32 v51, v51, v104
	v_mul_f32_e32 v52, v69, v50
	v_mul_f32_e32 v52, v52, v105
	v_mul_f32_e32 v53, v67, v50
	v_cvt_pk_bf16_f32 v52, v51, v52
	v_mul_f32_e32 v51, v66, v50
	v_mul_f32_e32 v53, v53, v107
	v_mul_f32_e32 v51, v51, v106
	v_cvt_pk_bf16_f32 v53, v51, v53
	ds_write_b64 v244, v[52:53] offset:32
	v_mul_f32_e32 v51, v64, v50
	s_waitcnt vmcnt(0)
	v_mul_f32_e32 v51, v51, v108
	v_mul_f32_e32 v52, v65, v50
	v_mul_f32_e32 v52, v52, v109
	v_cvt_pk_bf16_f32 v52, v51, v52
	v_mul_f32_e32 v46, v46, v110
	v_mul_f32_e32 v47, v47, v111
	v_cvt_pk_bf16_f32 v53, v46, v47
	ds_write_b64 v244, v[52:53] offset:48
	v_mul_f32_e32 v46, v48, v50
	v_mul_f32_e32 v47, v49, v50
	s_waitcnt vmcnt(0)
	v_mul_f32_e32 v46, v46, v112
	v_mul_f32_e32 v47, v47, v113
	v_cvt_pk_bf16_f32 v46, v46, v47
	v_mul_f32_e32 v44, v44, v114
	v_mul_f32_e32 v45, v45, v115
	v_cvt_pk_bf16_f32 v47, v44, v45
	ds_write_b64 v244, v[46:47] offset:64
	s_waitcnt vmcnt(0)
	v_mul_f32_e32 v42, v42, v116
	v_mul_f32_e32 v43, v43, v117
	v_cvt_pk_bf16_f32 v42, v42, v43
	v_mul_f32_e32 v40, v40, v118
	v_mul_f32_e32 v41, v41, v119
	v_cvt_pk_bf16_f32 v43, v40, v41
	ds_write_b64 v244, v[42:43] offset:80
	s_waitcnt vmcnt(0)
	v_mul_f32_e32 v38, v38, v120
	v_mul_f32_e32 v39, v39, v121
	v_cvt_pk_bf16_f32 v38, v38, v39
	v_mul_f32_e32 v36, v36, v122
	v_mul_f32_e32 v37, v37, v123
	v_cvt_pk_bf16_f32 v39, v36, v37
	ds_write_b64 v244, v[38:39] offset:96
	s_waitcnt vmcnt(0)
	v_mul_f32_e32 v34, v34, v124
	v_mul_f32_e32 v35, v35, v125
	v_cvt_pk_bf16_f32 v34, v34, v35
	v_mul_f32_e32 v32, v32, v126
	v_mul_f32_e32 v33, v33, v127
	v_cvt_pk_bf16_f32 v35, v32, v33
	ds_write_b64 v244, v[34:35] offset:112
	ds_read2_b32 v[32:33], v235 offset0:32 offset1:96
	v_add_u32_e32 v35, 0x80, v235
	s_waitcnt lgkmcnt(0)
	v_add_f32_e32 v32, 0, v32
	v_add_f32_e32 v34, v32, v33
	ds_read2_b32 v[32:33], v235 offset0:160 offset1:224
	s_waitcnt lgkmcnt(0)
	v_add_f32_e32 v32, v34, v32
	v_add_f32_e32 v34, v32, v33
	ds_read2st64_b32 v[32:33], v35 offset0:4 offset1:5
	s_waitcnt lgkmcnt(0)
	v_add_f32_e32 v32, v34, v32
	v_add_f32_e32 v34, v32, v33
	ds_read2st64_b32 v[32:33], v35 offset0:6 offset1:7
	s_waitcnt lgkmcnt(0)
	v_add_f32_e32 v32, v34, v32
	v_add_f32_e32 v32, v32, v33
	v_fmamk_f32 v32, v32, 0x3b000000, v178
	v_cmp_gt_f32_e32 vcc, s29, v32
	v_mul_f32_e32 v33, 0x4b800000, v32
	s_nop 0
	v_cndmask_b32_e32 v32, v32, v33, vcc
	v_rsq_f32_e32 v32, v32
	s_nop 0
	v_mul_f32_e32 v33, 0x45800000, v32
	v_cndmask_b32_e32 v32, v32, v33, vcc
	v_mul_f32_e32 v16, v16, v32
	v_mul_f32_e32 v17, v17, v32
	v_mul_f32_e32 v20, v20, v32
	v_mul_f32_e32 v0, v0, v32
	v_mul_f32_e32 v1, v1, v32
	v_mul_f32_e32 v4, v4, v32
	s_waitcnt vmcnt(0)
; __device__ __forceinline__ unsigned cvt_pk_bf16(float lo, float hi) { unsigned r; asm volatile("v_cvt_pk_bf16_f32 %0, %1, %2" : "=v"(r) : "v"(lo), "v"(hi)); return r; }
; #define LAS __attribute__((address_space(3)))
; #define LDS_WAIT() asm volatile("s_waitcnt lgkmcnt(0)" ::: "memory")
; __device__ __forceinline__ void attn_units(LAS unsigned char* lds, const bf16* QB, const bf16* KB, const bf16* VT, const bf16* VTc, bf16* MIX, const float* sink, const float* gmix,
;                                            int nunits, int G, int vb, int tid) {
;     ...
;             for (int dt = 0; dt < 2; ++dt)
; #pragma unroll
;                 for (int rg = 0; rg < 4; ++rg) { const f32x4 gm = *(const f32x4*)(gmix + wave * 64 + dt * 32 + rg * 8 + hh * 4);
;                     v2u w; w.x = cvt_pk_bf16(o[qs][dt][4 * rg] * rn * gm[0], o[qs][dt][4 * rg + 1] * rn * gm[1]); w.y = cvt_pk_bf16(o[qs][dt][4 * rg + 2] * rn * gm[2], o[qs][dt][4 * rg + 3] * rn * gm[3]);
;                     *(LAS v2u*)(otile + (qs * 32 + c) * 72 + dt * 32 + rg * 8 + hh * 4) = w; } }
;         LDS_WAIT();
; #pragma unroll
;         for (int it = 0; it < 8; ++it) { const int r = it * 8 + (lane >> 3), ch = lane & 7; const v4u v = *(const LAS v4u*)(otile + r * 72 + ch * 8);
;             *(v4u*)(MIX + (qrow0 + r) * 1024 + wave * 64 + ch * 8) = v; }
	v_mul_f32_e32 v16, v96, v16
	v_mul_f32_e32 v17, v97, v17
	v_cvt_pk_bf16_f32 v16, v16, v17
	v_mul_f32_e32 v17, v18, v32
	v_mul_f32_e32 v17, v98, v17
	v_mul_f32_e32 v18, v19, v32
	v_mul_f32_e32 v18, v99, v18
	v_cvt_pk_bf16_f32 v17, v17, v18
	ds_write_b64 v244, v[16:17] offset:4608
	s_waitcnt vmcnt(0)
	v_mul_f32_e32 v16, v100, v20
	v_mul_f32_e32 v20, v21, v32
	v_mul_f32_e32 v17, v101, v20
	v_cvt_pk_bf16_f32 v16, v16, v17
	v_mul_f32_e32 v17, v22, v32
	v_mul_f32_e32 v17, v102, v17
	v_mul_f32_e32 v18, v23, v32
	v_mul_f32_e32 v18, v103, v18
	v_cvt_pk_bf16_f32 v17, v17, v18
	ds_write_b64 v244, v[16:17] offset:4624
	v_mul_f32_e32 v20, v24, v32
	s_waitcnt vmcnt(0)
	v_mul_f32_e32 v16, v20, v104
	v_mul_f32_e32 v20, v25, v32
	v_mul_f32_e32 v17, v20, v105
	v_cvt_pk_bf16_f32 v16, v16, v17
	v_mul_f32_e32 v17, v26, v32
	v_mul_f32_e32 v17, v17, v106
	v_mul_f32_e32 v18, v27, v32
	v_mul_f32_e32 v18, v18, v107
	v_cvt_pk_bf16_f32 v17, v17, v18
	ds_write_b64 v244, v[16:17] offset:4640
	v_mul_f32_e32 v20, v28, v32
	s_waitcnt vmcnt(0)
	v_mul_f32_e32 v16, v20, v108
	v_mul_f32_e32 v20, v29, v32
	v_mul_f32_e32 v17, v20, v109
	v_cvt_pk_bf16_f32 v16, v16, v17
	v_mul_f32_e32 v17, v30, v32
	v_mul_f32_e32 v17, v17, v110
	v_mul_f32_e32 v18, v31, v32
	v_mul_f32_e32 v18, v18, v111
	v_cvt_pk_bf16_f32 v17, v17, v18
	ds_write_b64 v244, v[16:17] offset:4656
	s_waitcnt vmcnt(0)
	v_mul_f32_e32 v0, v0, v112
	v_mul_f32_e32 v1, v1, v113
	v_cvt_pk_bf16_f32 v0, v0, v1
	v_mul_f32_e32 v1, v2, v32
	v_mul_f32_e32 v1, v1, v114
	v_mul_f32_e32 v2, v3, v32
	v_mul_f32_e32 v2, v2, v115
	v_cvt_pk_bf16_f32 v1, v1, v2
	ds_write_b64 v244, v[0:1] offset:4672
	s_waitcnt vmcnt(0)
	v_mul_f32_e32 v0, v4, v116
	v_mul_f32_e32 v4, v5, v32
	v_mul_f32_e32 v1, v4, v117
	v_cvt_pk_bf16_f32 v0, v0, v1
	v_mul_f32_e32 v1, v6, v32
	v_mul_f32_e32 v1, v1, v118
	v_mul_f32_e32 v2, v7, v32
	v_mul_f32_e32 v2, v2, v119
	v_cvt_pk_bf16_f32 v1, v1, v2
	ds_write_b64 v244, v[0:1] offset:4688
	v_mul_f32_e32 v4, v8, v32
	s_waitcnt vmcnt(0)
	v_mul_f32_e32 v0, v4, v120
	v_mul_f32_e32 v4, v9, v32
	v_mul_f32_e32 v1, v4, v121
	v_cvt_pk_bf16_f32 v0, v0, v1
	v_mul_f32_e32 v1, v10, v32
	v_mul_f32_e32 v1, v1, v122
	v_mul_f32_e32 v2, v11, v32
	v_mul_f32_e32 v2, v2, v123
	v_cvt_pk_bf16_f32 v1, v1, v2
	ds_write_b64 v244, v[0:1] offset:4704
	v_mul_f32_e32 v4, v12, v32
	s_waitcnt vmcnt(0)
	v_mul_f32_e32 v0, v4, v124
	v_mul_f32_e32 v4, v13, v32
	v_mul_f32_e32 v1, v4, v125
	v_cvt_pk_bf16_f32 v0, v0, v1
	v_mul_f32_e32 v1, v14, v32
	v_mul_f32_e32 v1, v1, v126
	v_mul_f32_e32 v2, v15, v32
	v_mul_f32_e32 v2, v2, v127
	v_cvt_pk_bf16_f32 v1, v1, v2
	ds_write_b64 v244, v[0:1] offset:4720
	s_waitcnt lgkmcnt(0)
	ds_read_b128 v[96:99], v245
	ds_read_b128 v[100:103], v246
	ds_read_b128 v[104:107], v246 offset:1152
	ds_read_b128 v[108:111], v246 offset:2304
	ds_read_b128 v[112:115], v246 offset:3456
	ds_read_b128 v[116:119], v246 offset:4608
	ds_read_b128 v[120:123], v246 offset:5760
	ds_read_b128 v[124:127], v246 offset:6912
	v_lshl_add_u64 v[4:5], s[10:11], 0, v[194:195]
	v_lshlrev_b64 v[4:5], 11, v[4:5]
	v_lshl_add_u64 v[4:5], v[196:197], 0, v[4:5]
	s_waitcnt lgkmcnt(7)
	global_store_dwordx4 v[4:5], v[96:99], off
	v_lshl_add_u64 v[4:5], s[10:11], 0, v[214:215]
	v_lshlrev_b64 v[4:5], 11, v[4:5]
	v_lshl_add_u64 v[4:5], v[196:197], 0, v[4:5]
	s_waitcnt lgkmcnt(6)
	global_store_dwordx4 v[4:5], v[100:103], off
	v_lshl_add_u64 v[4:5], s[10:11], 0, v[216:217]
	v_lshlrev_b64 v[4:5], 11, v[4:5]
	v_lshl_add_u64 v[4:5], v[196:197], 0, v[4:5]
	s_waitcnt lgkmcnt(5)
	global_store_dwordx4 v[4:5], v[104:107], off
	v_lshl_add_u64 v[4:5], s[10:11], 0, v[218:219]
	v_lshlrev_b64 v[4:5], 11, v[4:5]
	v_lshl_add_u64 v[4:5], v[196:197], 0, v[4:5]
	s_waitcnt lgkmcnt(4)
	global_store_dwordx4 v[4:5], v[108:111], off
	v_lshl_add_u64 v[4:5], s[10:11], 0, v[220:221]
	v_lshlrev_b64 v[4:5], 11, v[4:5]
	v_lshl_add_u64 v[4:5], v[196:197], 0, v[4:5]
	s_waitcnt lgkmcnt(3)
	global_store_dwordx4 v[4:5], v[112:115], off
	v_lshl_add_u64 v[4:5], s[10:11], 0, v[222:223]
	v_lshlrev_b64 v[4:5], 11, v[4:5]
	v_lshl_add_u64 v[4:5], v[196:197], 0, v[4:5]
	s_waitcnt lgkmcnt(2)
	global_store_dwordx4 v[4:5], v[116:119], off
	v_lshl_add_u64 v[4:5], s[10:11], 0, v[224:225]
	v_lshlrev_b64 v[4:5], 11, v[4:5]
	v_lshl_add_u64 v[4:5], v[196:197], 0, v[4:5]
	s_waitcnt lgkmcnt(1)
	global_store_dwordx4 v[4:5], v[120:123], off
	v_lshl_add_u64 v[4:5], s[10:11], 0, v[226:227]
	v_lshlrev_b64 v[4:5], 11, v[4:5]
	v_lshl_add_u64 v[4:5], v[196:197], 0, v[4:5]
	s_waitcnt lgkmcnt(0)
	global_store_dwordx4 v[4:5], v[124:127], off
	s_cbranch_scc0 .LBB0_338

; __device__ __forceinline__ void attn_units(LAS unsigned char* lds, const bf16* QB, const bf16* KB, const bf16* VT, const bf16* VTc, bf16* MIX, const float* sink, const float* gmix,
;                                            int nunits, int G, int vb, int tid) {
;     ...
;         float ssq[2];
; #pragma unroll
;         for (int qs = 0; qs < 2; ++qs) { const float inv = 1.f / lrun[qs]; float ss = 0.f;
; #pragma unroll
;             for (int dt = 0; dt < 2; ++dt) { o[qs][dt] = o[qs][dt] * inv;
; #pragma unroll
;                 for (int r = 0; r < 16; ++r) ss += o[qs][dt][r] * o[qs][dt][r]; }
;             { auto rr = __builtin_amdgcn_permlane32_swap(__float_as_uint(ss), __float_as_uint(ss), false, false); ss = __uint_as_float(rr[0]) + __uint_as_float(rr[1]); }
;             ssq[qs] = ss; if (hh == 0) red[wave * 64 + qs * 32 + c] = ss; }
;     ...
;                 for (int rg = 0; rg < 4; ++rg) { const f32x4 gm = *(const f32x4*)(gmix + wave * 64 + dt * 32 + rg * 8 + hh * 4);
.LBB0_334:
	global_load_dwordx4 v[96:99], v[192:193], off
	global_load_dwordx4 v[100:103], v[192:193], off offset:32
	global_load_dwordx4 v[104:107], v[192:193], off offset:64
	global_load_dwordx4 v[108:111], v[192:193], off offset:96
	global_load_dwordx4 v[112:115], v[192:193], off offset:128
	global_load_dwordx4 v[116:119], v[192:193], off offset:160
	global_load_dwordx4 v[120:123], v[192:193], off offset:192
	global_load_dwordx4 v[124:127], v[192:193], off offset:224
	v_div_scale_f32 v64, s[4:5], v249, v249, 1.0
	v_rcp_f32_e32 v65, v64
	v_div_scale_f32 v66, vcc, 1.0, v249, 1.0
	v_fma_f32 v67, -v64, v65, 1.0
	v_fmac_f32_e32 v65, v67, v65
	v_mul_f32_e32 v67, v66, v65
	v_fma_f32 v68, -v64, v67, v66
	v_fmac_f32_e32 v67, v68, v65
	v_fma_f32 v64, -v64, v67, v66
	v_div_fmas_f32 v64, v64, v65, v67
	v_div_fixup_f32 v80, v64, v249, 1.0
	v_pk_mul_f32 v[76:77], v[32:33], v[80:81] op_sel_hi:[1,0]
	v_pk_mul_f32 v[74:75], v[34:35], v[80:81] op_sel_hi:[1,0]
	v_mul_f32_e32 v78, v77, v77
	v_fmac_f32_e32 v78, v76, v76
	v_fmac_f32_e32 v78, v74, v74
	v_pk_mul_f32 v[72:73], v[36:37], v[80:81] op_sel_hi:[1,0]
	v_fmac_f32_e32 v78, v75, v75
	v_fmac_f32_e32 v78, v72, v72
	v_pk_mul_f32 v[70:71], v[38:39], v[80:81] op_sel_hi:[1,0]
	v_fmac_f32_e32 v78, v73, v73
	v_fmac_f32_e32 v78, v70, v70
	v_pk_mul_f32 v[68:69], v[40:41], v[80:81] op_sel_hi:[1,0]
	v_fmac_f32_e32 v78, v71, v71
	v_fmac_f32_e32 v78, v68, v68
	v_pk_mul_f32 v[66:67], v[42:43], v[80:81] op_sel_hi:[1,0]
	v_fmac_f32_e32 v78, v69, v69
	v_fmac_f32_e32 v78, v66, v66
	v_pk_mul_f32 v[64:65], v[44:45], v[80:81] op_sel_hi:[1,0]
	v_fmac_f32_e32 v78, v67, v67
	v_fmac_f32_e32 v78, v64, v64
	v_pk_mul_f32 v[46:47], v[46:47], v[80:81] op_sel_hi:[1,0]
	v_fmac_f32_e32 v78, v65, v65
	v_fmac_f32_e32 v78, v46, v46
	v_fmac_f32_e32 v78, v47, v47
	v_pk_mul_f32 v[48:49], v[48:49], v[80:81] op_sel_hi:[1,0]
	v_pk_mul_f32 v[44:45], v[50:51], v[80:81] op_sel_hi:[1,0]
	v_fmac_f32_e32 v78, v48, v48
	v_fmac_f32_e32 v78, v49, v49
	v_fmac_f32_e32 v78, v44, v44
	v_pk_mul_f32 v[42:43], v[52:53], v[80:81] op_sel_hi:[1,0]
	v_fmac_f32_e32 v78, v45, v45
	v_fmac_f32_e32 v78, v42, v42
	v_pk_mul_f32 v[40:41], v[54:55], v[80:81] op_sel_hi:[1,0]
	v_fmac_f32_e32 v78, v43, v43
	v_fmac_f32_e32 v78, v40, v40
	v_pk_mul_f32 v[38:39], v[56:57], v[80:81] op_sel_hi:[1,0]
	v_fmac_f32_e32 v78, v41, v41
	v_fmac_f32_e32 v78, v38, v38
	v_pk_mul_f32 v[36:37], v[58:59], v[80:81] op_sel_hi:[1,0]
	v_fmac_f32_e32 v78, v39, v39
	v_fmac_f32_e32 v78, v36, v36
	v_pk_mul_f32 v[34:35], v[60:61], v[80:81] op_sel_hi:[1,0]
	v_fmac_f32_e32 v78, v37, v37
	v_fmac_f32_e32 v78, v34, v34
	v_pk_mul_f32 v[32:33], v[62:63], v[80:81] op_sel_hi:[1,0]
	v_fmac_f32_e32 v78, v35, v35
	v_fmac_f32_e32 v78, v32, v32
	v_fmac_f32_e32 v78, v33, v33
	v_mov_b32_e32 v50, v78
	s_nop 1
	v_permlane32_swap_b32_e32 v78, v50
	s_and_saveexec_b64 s[4:5], s[6:7]
	v_add_f32_e32 v50, v78, v50
	ds_write_b32 v236, v50
	s_or_b64 exec, exec, s[4:5]
	v_div_scale_f32 v50, s[4:5], v247, v247, 1.0
	v_rcp_f32_e32 v51, v50
	v_div_scale_f32 v52, vcc, 1.0, v247, 1.0
	v_fma_f32 v53, -v50, v51, 1.0
	v_fmac_f32_e32 v51, v53, v51
	v_mul_f32_e32 v53, v52, v51
	v_fma_f32 v54, -v50, v53, v52
	v_fmac_f32_e32 v53, v54, v51
	v_fma_f32 v50, -v50, v53, v52
	v_div_fmas_f32 v50, v50, v51, v53
	v_div_fixup_f32 v52, v50, v247, 1.0
	v_pk_mul_f32 v[16:17], v[16:17], v[52:53] op_sel_hi:[1,0]
	v_pk_mul_f32 v[18:19], v[18:19], v[52:53] op_sel_hi:[1,0]
	v_mul_f32_e32 v50, v17, v17
	v_fmac_f32_e32 v50, v16, v16
	v_fmac_f32_e32 v50, v18, v18
	v_pk_mul_f32 v[20:21], v[20:21], v[52:53] op_sel_hi:[1,0]
	v_fmac_f32_e32 v50, v19, v19
	v_fmac_f32_e32 v50, v20, v20
	v_pk_mul_f32 v[22:23], v[22:23], v[52:53] op_sel_hi:[1,0]
	v_fmac_f32_e32 v50, v21, v21
	v_fmac_f32_e32 v50, v22, v22
	v_pk_mul_f32 v[24:25], v[24:25], v[52:53] op_sel_hi:[1,0]
	v_fmac_f32_e32 v50, v23, v23
	v_fmac_f32_e32 v50, v24, v24
	v_pk_mul_f32 v[26:27], v[26:27], v[52:53] op_sel_hi:[1,0]
	v_fmac_f32_e32 v50, v25, v25
	v_fmac_f32_e32 v50, v26, v26
	v_pk_mul_f32 v[28:29], v[28:29], v[52:53] op_sel_hi:[1,0]
	v_fmac_f32_e32 v50, v27, v27
	v_fmac_f32_e32 v50, v28, v28
	v_pk_mul_f32 v[30:31], v[30:31], v[52:53] op_sel_hi:[1,0]
	v_fmac_f32_e32 v50, v29, v29
	v_fmac_f32_e32 v50, v30, v30
	v_fmac_f32_e32 v50, v31, v31
	v_pk_mul_f32 v[0:1], v[0:1], v[52:53] op_sel_hi:[1,0]
	v_pk_mul_f32 v[2:3], v[2:3], v[52:53] op_sel_hi:[1,0]
	v_fmac_f32_e32 v50, v0, v0
	v_fmac_f32_e32 v50, v1, v1
	v_fmac_f32_e32 v50, v2, v2
	v_pk_mul_f32 v[4:5], v[4:5], v[52:53] op_sel_hi:[1,0]
	v_fmac_f32_e32 v50, v3, v3
	v_fmac_f32_e32 v50, v4, v4
	v_pk_mul_f32 v[6:7], v[6:7], v[52:53] op_sel_hi:[1,0]
	v_fmac_f32_e32 v50, v5, v5
	v_fmac_f32_e32 v50, v6, v6
	v_pk_mul_f32 v[8:9], v[8:9], v[52:53] op_sel_hi:[1,0]
	v_fmac_f32_e32 v50, v7, v7
	v_fmac_f32_e32 v50, v8, v8
	v_pk_mul_f32 v[10:11], v[10:11], v[52:53] op_sel_hi:[1,0]
	v_fmac_f32_e32 v50, v9, v9
	v_fmac_f32_e32 v50, v10, v10
	v_pk_mul_f32 v[12:13], v[12:13], v[52:53] op_sel_hi:[1,0]
	v_fmac_f32_e32 v50, v11, v11
	v_fmac_f32_e32 v50, v12, v12
	v_pk_mul_f32 v[14:15], v[14:15], v[52:53] op_sel_hi:[1,0]
	v_fmac_f32_e32 v50, v13, v13
	v_fmac_f32_e32 v50, v14, v14
	v_fmac_f32_e32 v50, v15, v15
	v_mov_b32_e32 v51, v50
	s_nop 1
	v_permlane32_swap_b32_e32 v50, v51
	s_and_saveexec_b64 s[4:5], s[6:7]
	v_readlane_b32 s40, v255, 5
	v_readlane_b32 s41, v255, 6
	s_cbranch_execz .LBB0_293
	v_add_f32_e32 v50, v50, v51
	ds_write_b32 v236, v50 offset:128
	s_branch .LBB0_293

; __device__ __forceinline__ unsigned cvt_pk_bf16(float lo, float hi) { unsigned r; asm volatile("v_cvt_pk_bf16_f32 %0, %1, %2" : "=v"(r) : "v"(lo), "v"(hi)); return r; }
; #define LAS __attribute__((address_space(3)))
; __device__ __forceinline__ void sgu_units(LAS unsigned char* lds, const bf16* UB, const bf16* GVT, const bf16* GVTc, bf16* MIX, const float* wsgu, const float* bsgu, const float* gsgu, const float* gmix,
;                                           int nchunks, int G, int bid, int tid) {
;     ...
;         __syncthreads();
;         LAS bf16* otile = (LAS bf16*)(lds + 8192 + wave * 9216);
; #pragma unroll
;         for (int ps = 0; ps < 2; ++ps) { const int p = ph * 64 + ps * 32 + c;
;             const float rn = rsqrtf((red2[p] + red2[128 + p] + red2[256 + p] + red2[384 + p]) * (1.f / 256.f) + EPSN);
; #pragma unroll
;             for (int dt = 0; dt < 2; ++dt)
; #pragma unroll
;                 for (int rg = 0; rg < 4; ++rg) { const int d0 = dt * 32 + rg * 8 + h2 * 4; const f32x4 gm = *(const f32x4*)(gmix + 512 + hd * 64 + d0);
;                     v2u w; w.x = cvt_pk_bf16(o[dt][ps][4 * rg] * rn * gm[0], o[dt][ps][4 * rg + 1] * rn * gm[1]); w.y = cvt_pk_bf16(o[dt][ps][4 * rg + 2] * rn * gm[2], o[dt][ps][4 * rg + 3] * rn * gm[3]);
;                     *(LAS v2u*)(otile + (ps * 32 + c) * 72 + d0) = w; } }
.LBB0_341:
	s_or_b64 exec, exec, s[8:9]
	s_waitcnt lgkmcnt(0)
	s_barrier
	global_load_dwordx4 v[128:131], v[196:197], off offset:2048
	global_load_dwordx4 v[132:135], v[196:197], off offset:2080
	global_load_dwordx4 v[136:139], v[196:197], off offset:2112
	global_load_dwordx4 v[140:143], v[196:197], off offset:2144
	global_load_dwordx4 v[144:147], v[196:197], off offset:2176
	global_load_dwordx4 v[148:151], v[196:197], off offset:2208
	global_load_dwordx4 v[214:217], v[196:197], off offset:2240
	global_load_dwordx4 v[218:221], v[196:197], off offset:2272
	ds_read2st64_b32 v[10:11], v187 offset0:16 offset1:18
	s_or_b64 s[6:7], s[6:7], s[0:1]
	s_add_i32 s11, s11, s62
	s_cmp_lt_i32 s11, s63
	s_waitcnt lgkmcnt(0)
	v_add_f32_e32 v12, v10, v11
	ds_read2st64_b32 v[10:11], v187 offset0:20 offset1:22
	s_waitcnt lgkmcnt(0)
	v_add_f32_e32 v10, v12, v10
	v_add_f32_e32 v10, v10, v11
	v_fmamk_f32 v10, v10, 0x3b800000, v178
	v_cmp_gt_f32_e32 vcc, s29, v10
	v_mul_f32_e32 v11, 0x4b800000, v10
	s_nop 0
	v_cndmask_b32_e32 v10, v10, v11, vcc
	v_rsq_f32_e32 v10, v10
	s_nop 0
	v_mul_f32_e32 v11, 0x45800000, v10
	v_cndmask_b32_e32 v14, v10, v11, vcc
	v_mul_f32_e32 v15, v212, v14
	s_waitcnt vmcnt(0)
	v_mul_f32_e32 v10, v128, v15
	v_mul_f32_e32 v15, v211, v14
	v_mul_f32_e32 v11, v129, v15
	v_cvt_pk_bf16_f32 v10, v10, v11
	v_mul_f32_e32 v11, v209, v14
	v_mul_f32_e32 v11, v130, v11
	v_mul_f32_e32 v12, v207, v14
	v_mul_f32_e32 v12, v131, v12
	v_cvt_pk_bf16_f32 v11, v11, v12
	ds_write_b64 v163, v[10:11] offset:8192
	v_mul_f32_e32 v15, v210, v14
	s_waitcnt vmcnt(0)
	v_mul_f32_e32 v10, v132, v15
	v_mul_f32_e32 v15, v208, v14
	v_mul_f32_e32 v11, v133, v15
	v_cvt_pk_bf16_f32 v10, v10, v11
	v_mul_f32_e32 v11, v206, v14
	v_mul_f32_e32 v11, v134, v11
	v_mul_f32_e32 v12, v205, v14
	v_mul_f32_e32 v12, v135, v12
	v_cvt_pk_bf16_f32 v11, v11, v12
	ds_write_b64 v163, v[10:11] offset:8208
	v_mul_f32_e32 v15, v204, v14
	s_waitcnt vmcnt(0)
	v_mul_f32_e32 v10, v15, v136
	v_mul_f32_e32 v15, v203, v14
	v_mul_f32_e32 v11, v15, v137
	v_cvt_pk_bf16_f32 v10, v10, v11
	v_mul_f32_e32 v11, v202, v14
	v_mul_f32_e32 v11, v11, v138
	v_mul_f32_e32 v12, v191, v14
	v_mul_f32_e32 v12, v12, v139
	v_cvt_pk_bf16_f32 v11, v11, v12
	ds_write_b64 v163, v[10:11] offset:8224
	v_mul_f32_e32 v15, v201, v14
	s_waitcnt vmcnt(0)
	v_mul_f32_e32 v10, v15, v140
	v_mul_f32_e32 v15, v159, v14
	v_mul_f32_e32 v11, v15, v141
	v_cvt_pk_bf16_f32 v10, v10, v11
	v_mul_f32_e32 v11, v158, v14
	v_mul_f32_e32 v11, v11, v142
	v_mul_f32_e32 v12, v157, v14
	v_mul_f32_e32 v12, v12, v143
	v_cvt_pk_bf16_f32 v11, v11, v12
	ds_write_b64 v163, v[10:11] offset:8240
	v_mul_f32_e32 v15, v156, v14
	s_waitcnt vmcnt(0)
	v_mul_f32_e32 v10, v15, v144
	v_mul_f32_e32 v15, v155, v14
	v_mul_f32_e32 v11, v15, v145
	v_cvt_pk_bf16_f32 v10, v10, v11
	v_mul_f32_e32 v11, v154, v14
	v_mul_f32_e32 v11, v11, v146
	v_mul_f32_e32 v12, v153, v14
	v_mul_f32_e32 v12, v12, v147
	v_cvt_pk_bf16_f32 v11, v11, v12
	ds_write_b64 v163, v[10:11] offset:8256
	v_mul_f32_e32 v15, v152, v14
	s_waitcnt vmcnt(0)
	v_mul_f32_e32 v10, v15, v148
	v_mul_f32_e32 v15, v63, v14
	v_mul_f32_e32 v11, v15, v149
	v_cvt_pk_bf16_f32 v10, v10, v11
	v_mul_f32_e32 v11, v62, v14
	v_mul_f32_e32 v11, v11, v150
	v_mul_f32_e32 v12, v61, v14
	v_mul_f32_e32 v12, v12, v151
	v_cvt_pk_bf16_f32 v11, v11, v12
	ds_write_b64 v163, v[10:11] offset:8272
	v_mul_f32_e32 v15, v60, v14
	s_waitcnt vmcnt(0)
	v_mul_f32_e32 v10, v15, v214
	v_mul_f32_e32 v15, v59, v14
	v_mul_f32_e32 v11, v15, v215
	v_cvt_pk_bf16_f32 v10, v10, v11
	v_mul_f32_e32 v11, v58, v14
	v_mul_f32_e32 v11, v11, v216
	v_mul_f32_e32 v12, v57, v14
	v_mul_f32_e32 v12, v12, v217
	v_cvt_pk_bf16_f32 v11, v11, v12
	ds_write_b64 v163, v[10:11] offset:8288
	v_mul_f32_e32 v15, v56, v14
	s_waitcnt vmcnt(0)
	v_mul_f32_e32 v10, v15, v218
	v_mul_f32_e32 v15, v44, v14
	v_mul_f32_e32 v11, v15, v219
	v_cvt_pk_bf16_f32 v10, v10, v11
	v_mul_f32_e32 v11, v43, v14
	v_mul_f32_e32 v11, v11, v220
	v_mul_f32_e32 v12, v42, v14
	v_mul_f32_e32 v12, v12, v221
	v_cvt_pk_bf16_f32 v11, v11, v12
	ds_write_b64 v163, v[10:11] offset:8304
	v_add_u32_e32 v12, 0x80, v187
	ds_read2st64_b32 v[10:11], v12 offset0:16 offset1:18
	s_waitcnt lgkmcnt(0)
	v_add_f32_e32 v13, v10, v11
	ds_read2st64_b32 v[10:11], v12 offset0:20 offset1:22
	s_waitcnt lgkmcnt(0)
	v_add_f32_e32 v10, v13, v10
	v_add_f32_e32 v10, v10, v11
	v_fmamk_f32 v10, v10, 0x3b800000, v178
	v_cmp_gt_f32_e32 vcc, s29, v10
	v_mul_f32_e32 v11, 0x4b800000, v10
	s_nop 0
	v_cndmask_b32_e32 v10, v10, v11, vcc
	v_rsq_f32_e32 v10, v10
	s_nop 0
	v_mul_f32_e32 v11, 0x45800000, v10
	v_cndmask_b32_e32 v14, v10, v11, vcc
	v_mul_f32_e32 v15, v41, v14
	v_mul_f32_e32 v0, v0, v14
	v_mul_f32_e32 v1, v1, v14
	v_mul_f32_e32 v4, v4, v14
	s_waitcnt vmcnt(0)
; __device__ __forceinline__ unsigned cvt_pk_bf16(float lo, float hi) { unsigned r; asm volatile("v_cvt_pk_bf16_f32 %0, %1, %2" : "=v"(r) : "v"(lo), "v"(hi)); return r; }
; #define LAS __attribute__((address_space(3)))
; #define LDS_WAIT() asm volatile("s_waitcnt lgkmcnt(0)" ::: "memory")
; __device__ __forceinline__ void sgu_units(LAS unsigned char* lds, const bf16* UB, const bf16* GVT, const bf16* GVTc, bf16* MIX, const float* wsgu, const float* bsgu, const float* gsgu, const float* gmix,
;                                           int nchunks, int G, int bid, int tid) {
;     ...
;             for (int dt = 0; dt < 2; ++dt)
; #pragma unroll
;                 for (int rg = 0; rg < 4; ++rg) { const int d0 = dt * 32 + rg * 8 + h2 * 4; const f32x4 gm = *(const f32x4*)(gmix + 512 + hd * 64 + d0);
;                     v2u w; w.x = cvt_pk_bf16(o[dt][ps][4 * rg] * rn * gm[0], o[dt][ps][4 * rg + 1] * rn * gm[1]); w.y = cvt_pk_bf16(o[dt][ps][4 * rg + 2] * rn * gm[2], o[dt][ps][4 * rg + 3] * rn * gm[3]);
;                     *(LAS v2u*)(otile + (ps * 32 + c) * 72 + d0) = w; } }
;         LDS_WAIT();
; #pragma unroll
;         for (int it = 0; it < 8; ++it) { const int r = it * 8 + (lane >> 3), ch = lane & 7; const v4u v = *(const LAS v4u*)(otile + r * 72 + ch * 8);
;             *(v4u*)(MIX + ((size_t)chunk * 128 + ph * 64 + r) * 1024 + 512 + hd * 64 + ch * 8) = v; }
;         LDS_WAIT();
;         __syncthreads();
	v_mul_f32_e32 v10, v128, v15
	v_mul_f32_e32 v15, v40, v14
	v_mul_f32_e32 v11, v129, v15
	v_cvt_pk_bf16_f32 v10, v10, v11
	v_mul_f32_e32 v11, v39, v14
	v_mul_f32_e32 v11, v130, v11
	v_mul_f32_e32 v12, v38, v14
	v_mul_f32_e32 v12, v131, v12
	v_cvt_pk_bf16_f32 v11, v11, v12
	ds_write_b64 v171, v[10:11] offset:8192
	v_mul_f32_e32 v15, v37, v14
	s_waitcnt vmcnt(0)
	v_mul_f32_e32 v10, v132, v15
	v_mul_f32_e32 v15, v36, v14
	v_mul_f32_e32 v11, v133, v15
	v_cvt_pk_bf16_f32 v10, v10, v11
	v_mul_f32_e32 v11, v35, v14
	v_mul_f32_e32 v11, v134, v11
	v_mul_f32_e32 v12, v34, v14
	v_mul_f32_e32 v12, v135, v12
	v_cvt_pk_bf16_f32 v11, v11, v12
	ds_write_b64 v171, v[10:11] offset:8208
	v_mul_f32_e32 v15, v33, v14
	s_waitcnt vmcnt(0)
	v_mul_f32_e32 v10, v15, v136
	v_mul_f32_e32 v15, v32, v14
	v_mul_f32_e32 v11, v15, v137
	v_cvt_pk_bf16_f32 v10, v10, v11
	v_mul_f32_e32 v11, v25, v14
	v_mul_f32_e32 v11, v11, v138
	v_mul_f32_e32 v12, v24, v14
	v_mul_f32_e32 v12, v12, v139
	v_cvt_pk_bf16_f32 v11, v11, v12
	ds_write_b64 v171, v[10:11] offset:8224
	v_mul_f32_e32 v15, v23, v14
	s_waitcnt vmcnt(0)
	v_mul_f32_e32 v10, v15, v140
	v_mul_f32_e32 v15, v22, v14
	v_mul_f32_e32 v11, v15, v141
	v_cvt_pk_bf16_f32 v10, v10, v11
	v_mul_f32_e32 v11, v21, v14
	v_mul_f32_e32 v11, v11, v142
	v_mul_f32_e32 v12, v20, v14
	v_mul_f32_e32 v12, v12, v143
	v_cvt_pk_bf16_f32 v11, v11, v12
	ds_write_b64 v171, v[10:11] offset:8240
	s_waitcnt vmcnt(0)
	v_mul_f32_e32 v0, v0, v144
	v_mul_f32_e32 v1, v1, v145
	v_cvt_pk_bf16_f32 v0, v0, v1
	v_mul_f32_e32 v1, v2, v14
	v_mul_f32_e32 v1, v1, v146
	v_mul_f32_e32 v2, v3, v14
	v_mul_f32_e32 v2, v2, v147
	v_cvt_pk_bf16_f32 v1, v1, v2
	ds_write_b64 v171, v[0:1] offset:8256
	v_mul_f32_e32 v10, v26, v14
	s_waitcnt vmcnt(0)
	v_mul_f32_e32 v0, v10, v148
	v_mul_f32_e32 v10, v18, v14
	v_mul_f32_e32 v1, v10, v149
	v_cvt_pk_bf16_f32 v0, v0, v1
	v_mul_f32_e32 v1, v17, v14
	v_mul_f32_e32 v1, v1, v150
	v_mul_f32_e32 v2, v16, v14
	v_mul_f32_e32 v2, v2, v151
	v_cvt_pk_bf16_f32 v1, v1, v2
	ds_write_b64 v171, v[0:1] offset:8272
	v_mul_f32_e32 v10, v27, v14
	s_waitcnt vmcnt(0)
	v_mul_f32_e32 v0, v10, v214
	v_mul_f32_e32 v10, v19, v14
	v_mul_f32_e32 v1, v10, v215
	v_cvt_pk_bf16_f32 v0, v0, v1
	v_mul_f32_e32 v1, v9, v14
	v_mul_f32_e32 v1, v1, v216
	v_mul_f32_e32 v2, v8, v14
	v_mul_f32_e32 v2, v2, v217
	v_cvt_pk_bf16_f32 v1, v1, v2
	ds_write_b64 v171, v[0:1] offset:8288
	s_waitcnt vmcnt(0)
	v_mul_f32_e32 v0, v4, v218
	v_mul_f32_e32 v4, v5, v14
	v_mul_f32_e32 v1, v4, v219
	v_cvt_pk_bf16_f32 v0, v0, v1
	v_mul_f32_e32 v1, v6, v14
	v_mul_f32_e32 v1, v1, v220
	v_mul_f32_e32 v2, v7, v14
	v_mul_f32_e32 v2, v2, v221
	v_cvt_pk_bf16_f32 v1, v1, v2
	ds_write_b64 v171, v[0:1] offset:8304
	s_waitcnt lgkmcnt(0)
	ds_read_b128 v[128:131], v189 offset:8192
	ds_read_b128 v[132:135], v189 offset:9344
	ds_read_b128 v[136:139], v189 offset:10496
	ds_read_b128 v[140:143], v189 offset:11648
	ds_read_b128 v[144:147], v189 offset:12800
	ds_read_b128 v[148:151], v189 offset:13952
	ds_read_b128 v[214:217], v189 offset:15104
	ds_read_b128 v[218:221], v189 offset:16256
	v_mov_b32_e32 v5, s7
	v_or_b32_e32 v4, s6, v162
	v_lshlrev_b64 v[4:5], 11, v[4:5]
	v_lshl_add_u64 v[4:5], v[198:199], 0, v[4:5]
	s_waitcnt lgkmcnt(7)
	global_store_dwordx4 v[4:5], v[128:131], off offset:1024
	v_mov_b32_e32 v5, s7
	v_or_b32_e32 v4, s6, v170
	v_lshlrev_b64 v[4:5], 11, v[4:5]
	v_lshl_add_u64 v[4:5], v[198:199], 0, v[4:5]
	s_waitcnt lgkmcnt(6)
	global_store_dwordx4 v[4:5], v[132:135], off offset:1024
	v_mov_b32_e32 v5, s7
	v_or_b32_e32 v4, s6, v172
	v_lshlrev_b64 v[4:5], 11, v[4:5]
	v_lshl_add_u64 v[4:5], v[198:199], 0, v[4:5]
	s_waitcnt lgkmcnt(5)
	global_store_dwordx4 v[4:5], v[136:139], off offset:1024
	v_mov_b32_e32 v5, s7
	v_or_b32_e32 v4, s6, v174
	v_lshlrev_b64 v[4:5], 11, v[4:5]
	v_lshl_add_u64 v[4:5], v[198:199], 0, v[4:5]
	s_waitcnt lgkmcnt(4)
	global_store_dwordx4 v[4:5], v[140:143], off offset:1024
	v_mov_b32_e32 v5, s7
	v_or_b32_e32 v4, s6, v180
	v_lshlrev_b64 v[4:5], 11, v[4:5]
	v_lshl_add_u64 v[4:5], v[198:199], 0, v[4:5]
	s_waitcnt lgkmcnt(3)
	global_store_dwordx4 v[4:5], v[144:147], off offset:1024
	v_mov_b32_e32 v5, s7
	v_or_b32_e32 v4, s6, v186
	v_lshlrev_b64 v[4:5], 11, v[4:5]
	v_lshl_add_u64 v[4:5], v[198:199], 0, v[4:5]
	s_waitcnt lgkmcnt(2)
	global_store_dwordx4 v[4:5], v[148:151], off offset:1024
	v_mov_b32_e32 v5, s7
	v_or_b32_e32 v4, s6, v188
	v_lshlrev_b64 v[4:5], 11, v[4:5]
	v_lshl_add_u64 v[4:5], v[198:199], 0, v[4:5]
	s_waitcnt lgkmcnt(1)
	global_store_dwordx4 v[4:5], v[214:217], off offset:1024
	v_mov_b32_e32 v5, s7
	v_or_b32_e32 v4, s6, v190
	v_lshlrev_b64 v[4:5], 11, v[4:5]
	v_lshl_add_u64 v[4:5], v[198:199], 0, v[4:5]
	s_waitcnt lgkmcnt(0)
	global_store_dwordx4 v[4:5], v[218:221], off offset:1024
	s_waitcnt lgkmcnt(0)
	s_barrier
	s_cbranch_scc0 .LBB0_353
